# attention prologue: Q tile fetched with coalesced loads (6 per wave, split between the two waves sharing the rows), parked in LDS [32][400B] per row group, fragments read by ds_read_b128 after the pro
# speedup vs baseline: 1.0151x; 1.0115x over previous
; #define AT_LOAD(st) do { _Pragma("unroll") for (int e = 0; e < 3; ++e) pk[e] = *(const u32x4*)(kbase + (size_t)((st) * 64 + krow[e]) * 768 + kcol[e] * 8); \
;         _Pragma("unroll") for (int e = 0; e < 2; ++e) { const int c = tid + 512 * e; pv[e] = *(const u32x4*)(vbase + (size_t)(c >> 3) * SEQ + (st) * 64 + (c & 7) * 8); } } while (0)
; DI void attn_unit(const Params& p, int b, int h, int qb, LAS unsigned char* lds, int tid, int lane, int wave) {
;     ...
;     const int g = wave >> 2, w4 = wave & 3, r = lane & 31, hh = lane >> 5;
;     const int qr0 = qb * 128 + w4 * 32, nst = 2 * (qb + 1);
;     const size_t tokb = (size_t)b * SEQ;
;     bf16x8 qf[12];
;     { const bf16_t* qp = Q + (tokb + qr0 + r) * 768 + h * 192 + 8 * hh;
; #pragma unroll
;       for (int kk = 0; kk < 12; ++kk) qf[kk] = *(const bf16x8*)(qp + 16 * kk); }
;     f32x16 o[4];
; #pragma unroll
;     for (int i = 0; i < 4; ++i)
; #pragma unroll
;         for (int j = 0; j < 16; ++j) o[i][j] = 0.f;
;     float mrow = -INFINITY, lrow = 0.f;
;     const bf16_t* kbase = KB + tokb * 768 + h * 192;
;     const bf16_t* vbase = VT + (size_t)((b * 4 + h) * 128) * SEQ;
;     int krow[3], kcol[3];
; #pragma unroll
;     for (int e = 0; e < 3; ++e) { const int c = tid + 512 * e; krow[e] = c / 24; kcol[e] = c % 24; }
;     u32x4 pk[3], pv[2];
;     ...
;     AT_LOAD(0); AT_WRITE(0);
.LBB0_426:
	s_mov_b32 s3, s33
	v_mbcnt_lo_u32_b32 v183, -1, 0
	v_mbcnt_hi_u32_b32 v183, -1, v183
	s_mov_b32 s5, 0x2aaaaaab
	v_lshl_add_u32 v14, s3, 6, v183
	v_mul_hi_i32 v0, v14, s5
	v_lshrrev_b32_e32 v2, 31, v0
	v_ashrrev_i32_e32 v0, 2, v0
	v_add_u32_e32 v40, v0, v2
	s_bfe_u32 s4, s73, 0x20006
	s_bfe_u32 s2, s73, 0x20004
	v_mul_lo_u32 v0, v40, 24
	s_waitcnt vmcnt(0)
	v_add_u32_e32 v20, 0x200, v14
	s_lshl_b32 s0, s2, 20
	s_lshl_b32 s1, s4, 22
	v_sub_u32_e32 v41, v14, v0
	v_mul_hi_i32 v0, v20, s5
	s_or_b32 s92, s1, s0
	s_mov_b64 s[0:1], s[50:51]
	v_lshrrev_b32_e32 v2, 31, v0
	v_ashrrev_i32_e32 v0, 2, v0
	s_and_b32 s94, s73, 15
	v_add_u32_e32 v42, v0, v2
	s_xor_b32 s0, s94, 31
	s_and_b32 s20, s3, 3
	v_mul_lo_u32 v0, v42, 24
	s_lshl_b32 s6, s0, 7
	s_lshl_b32 s0, s20, 5
	s_mul_i32 s67, s2, 0xc0
	v_sub_u32_e32 v43, v20, v0
	v_add_u32_e32 v0, 0x400, v14
	s_or_b32 s36, s0, s6
	s_lshl_b32 s66, s4, 12
	s_lshl_b32 s0, s67, 1
	s_ashr_i32 s21, s3, 2
	s_mul_i32 s7, s4, 0x600000
	v_readlane_b32 s1, v254, 52
	v_mul_hi_i32 v2, v0, s5
	s_add_u32 s1, s1, s7
	v_readlane_b32 s4, v254, 53
	v_lshrrev_b32_e32 v3, 31, v2
	v_ashrrev_i32_e32 v2, 2, v2
	s_addc_u32 s4, s4, 0
	v_add_u32_e32 v44, v2, v3
	v_mul_lo_u32 v2, v44, 24
	s_add_u32 s52, s1, s0
	v_sub_u32_e32 v45, v0, v2
	s_addc_u32 s53, s4, 0
	v_lshlrev_b32_e32 v4, 3, v41
	v_lshlrev_b32_e32 v6, 3, v43
	v_mov_b64_e32 v[10:11], s[52:53]
	v_ashrrev_i32_e32 v5, 31, v4
	v_ashrrev_i32_e32 v7, 31, v6
	v_lshlrev_b32_e32 v12, 3, v45
	v_readlane_b32 s1, v254, 50
	v_mad_i64_i32 v[2:3], s[4:5], v40, s76, v[10:11]
	v_lshlrev_b64 v[22:23], 1, v[4:5]
	v_mad_i64_i32 v[4:5], s[4:5], v42, s76, v[10:11]
	v_lshlrev_b64 v[24:25], 1, v[6:7]
	v_ashrrev_i32_e32 v13, 31, v12
	s_add_u32 s74, s1, s92
	v_readlane_b32 s1, v254, 51
	v_lshlrev_b32_e32 v0, 4, v183
	v_ashrrev_i32_e32 v28, 3, v14
	v_lshl_add_u64 v[2:3], v[2:3], 0, v[22:23]
	v_lshl_add_u64 v[6:7], v[4:5], 0, v[24:25]
	v_mad_i64_i32 v[10:11], s[4:5], v44, s76, v[10:11]
	v_lshlrev_b64 v[26:27], 1, v[12:13]
	s_addc_u32 s75, s1, 0
	v_and_b32_e32 v0, 0x70, v0
	v_ashrrev_i32_e32 v29, 31, v28
	v_ashrrev_i32_e32 v32, 3, v20
	global_load_dwordx4 v[2:5], v[2:3], off
	s_nop 0
	global_load_dwordx4 v[6:9], v[6:7], off
	v_lshl_add_u64 v[10:11], v[10:11], 0, v[26:27]
	v_lshl_add_u64 v[18:19], s[74:75], 0, v[0:1]
	v_lshlrev_b64 v[30:31], 13, v[28:29]
	v_ashrrev_i32_e32 v33, 31, v32
	global_load_dwordx4 v[10:13], v[10:11], off
	v_lshl_add_u64 v[14:15], v[18:19], 0, v[30:31]
	v_lshlrev_b64 v[34:35], 13, v[32:33]
	v_and_b32_e32 v29, 31, v183
	v_readlane_b32 s4, v254, 48
	global_load_dwordx4 v[14:17], v[14:15], off
	v_lshl_add_u64 v[18:19], v[18:19], 0, v[34:35]
	v_or_b32_e32 v36, s66, v29
	v_readlane_b32 s5, v254, 49
	global_load_dwordx4 v[18:21], v[18:19], off
	v_ashrrev_i32_e32 v33, 5, v183
	v_or_b32_e32 v202, s36, v36
	v_mov_b64_e32 v[36:37], s[4:5]
	v_mad_u64_u32 v[36:37], s[4:5], v202, s76, v[36:37]
	s_mov_b32 s1, s93
	v_lshlrev_b32_e32 v38, 3, v33
	v_lshl_add_u64 v[36:37], v[36:37], 0, s[0:1]
	v_ashrrev_i32_e32 v39, 31, v38
	v_lshl_add_u64 v[36:37], v[38:39], 1, v[36:37]
	v_readfirstlane_b32 s0, v36
	v_readfirstlane_b32 s1, v37
	s_lshr_b32 vcc_hi, s3, 2
	s_mul_i32 vcc_lo, s20, 0x3200
	s_add_u32 vcc_lo, vcc_lo, 0x15800
	s_mulk_i32 vcc_hi, 0x180
	v_add_u32_e32 v78, vcc_hi, v183
	v_mul_u32_u24_e32 v79, 0xaaab, v78
	v_lshrrev_b32_e32 v79, 20, v79
	v_mul_u32_u24_e32 v80, 24, v79
	v_sub_u32_e32 v80, v78, v80
	v_lshlrev_b32_e32 v80, 4, v80
	v_mad_u32_u24 v81, v79, s76, v80
	v_mad_u32_u24 v66, v79, s77, v80
	v_add_u32_e32 v66, vcc_lo, v66
	global_load_dwordx4 v[130:133], v81, s[0:1]
	v_add_u32_e32 v78, 64, v78
	v_mul_u32_u24_e32 v79, 0xaaab, v78
	v_lshrrev_b32_e32 v79, 20, v79
	v_mul_u32_u24_e32 v80, 24, v79
	v_sub_u32_e32 v80, v78, v80
	v_lshlrev_b32_e32 v80, 4, v80
	v_mad_u32_u24 v81, v79, s76, v80
	v_mad_u32_u24 v67, v79, s77, v80
	v_add_u32_e32 v67, vcc_lo, v67
	global_load_dwordx4 v[134:137], v81, s[0:1]
	v_add_u32_e32 v78, 64, v78
	v_mul_u32_u24_e32 v79, 0xaaab, v78
	v_lshrrev_b32_e32 v79, 20, v79
	v_mul_u32_u24_e32 v80, 24, v79
	v_sub_u32_e32 v80, v78, v80
	v_lshlrev_b32_e32 v80, 4, v80
	v_mad_u32_u24 v81, v79, s76, v80
	v_mad_u32_u24 v68, v79, s77, v80
	v_add_u32_e32 v68, vcc_lo, v68
	global_load_dwordx4 v[138:141], v81, s[0:1]
	v_add_u32_e32 v78, 64, v78
	v_mul_u32_u24_e32 v79, 0xaaab, v78
	v_lshrrev_b32_e32 v79, 20, v79
	v_mul_u32_u24_e32 v80, 24, v79
	v_sub_u32_e32 v80, v78, v80
	v_lshlrev_b32_e32 v80, 4, v80
	v_mad_u32_u24 v81, v79, s76, v80
	v_mad_u32_u24 v69, v79, s77, v80
	v_add_u32_e32 v69, vcc_lo, v69
	global_load_dwordx4 v[142:145], v81, s[0:1]
	v_add_u32_e32 v78, 64, v78
	v_mul_u32_u24_e32 v79, 0xaaab, v78
	v_lshrrev_b32_e32 v79, 20, v79
	v_mul_u32_u24_e32 v80, 24, v79
	v_sub_u32_e32 v80, v78, v80
	v_lshlrev_b32_e32 v80, 4, v80
	v_mad_u32_u24 v81, v79, s76, v80
	v_mad_u32_u24 v70, v79, s77, v80
	v_add_u32_e32 v70, vcc_lo, v70
	global_load_dwordx4 v[146:149], v81, s[0:1]
	v_add_u32_e32 v78, 64, v78
	v_mul_u32_u24_e32 v79, 0xaaab, v78
	v_lshrrev_b32_e32 v79, 20, v79
	v_mul_u32_u24_e32 v80, 24, v79
	v_sub_u32_e32 v80, v78, v80
	v_lshlrev_b32_e32 v80, 4, v80
	v_mad_u32_u24 v81, v79, s76, v80
	v_mad_u32_u24 v71, v79, s77, v80
	v_add_u32_e32 v71, vcc_lo, v71
	global_load_dwordx4 v[150:153], v81, s[0:1]
	v_mul_lo_u32 v207, v40, s77
	v_lshlrev_b32_e32 v208, 4, v41
	v_add3_u32 v36, 0, v207, v208
	v_mul_lo_u32 v209, v42, s77
	v_lshlrev_b32_e32 v210, 4, v43
	v_mul_lo_u32 v211, v44, s77
	v_lshlrev_b32_e32 v212, 4, v45
	s_movk_i32 s0, 0x90
	v_bfe_u32 v222, v0, 4, 1
	v_and_b32_e32 v213, 0x60, v0
	v_lshl_or_b32 v213, v222, 3, v213
	v_mul_lo_u32 v214, v28, s0
	v_mul_lo_u32 v215, v32, s0
	s_lshl_b32 s56, s21, 5
	v_lshlrev_b32_e32 v182, 2, v33
	v_or_b32_e32 v205, s36, v29
	s_or_b32 s57, s36, 31
	s_or_b32 s59, s6, 64
	v_or_b32_e32 v30, v30, v0
	s_mov_b64 s[0:1], 0xe600080
	v_or_b32_e32 v34, v34, v0
	s_add_u32 s54, s7, 0xce18000
	s_addc_u32 s55, 0, 0
	v_mov_b32_e32 v0, 0x180
	s_mov_b32 s62, 0
	v_mov_b32_e32 v203, 0
	v_mov_b32_e32 v204, 0xff800000
	s_mov_b32 s63, 0
	s_waitcnt vmcnt(10)
; #define AT_LOAD(st) do { _Pragma("unroll") for (int e = 0; e < 3; ++e) pk[e] = *(const u32x4*)(kbase + (size_t)((st) * 64 + krow[e]) * 768 + kcol[e] * 8); \
;         _Pragma("unroll") for (int e = 0; e < 2; ++e) { const int c = tid + 512 * e; pv[e] = *(const u32x4*)(vbase + (size_t)(c >> 3) * SEQ + (st) * 64 + (c & 7) * 8); } } while (0)
; DI void attn_unit(const Params& p, int b, int h, int qb, LAS unsigned char* lds, int tid, int lane, int wave) {
;     ...
;     bf16x8 qf[12];
;     { const bf16_t* qp = Q + (tokb + qr0 + r) * 768 + h * 192 + 8 * hh;
; #pragma unroll
;       for (int kk = 0; kk < 12; ++kk) qf[kk] = *(const bf16x8*)(qp + 16 * kk); }
;     f32x16 o[4];
; #pragma unroll
;     for (int i = 0; i < 4; ++i)
; #pragma unroll
;         for (int j = 0; j < 16; ++j) o[i][j] = 0.f;
;     float mrow = -INFINITY, lrow = 0.f;
;     const bf16_t* kbase = KB + tokb * 768 + h * 192;
;     const bf16_t* vbase = VT + (size_t)((b * 4 + h) * 128) * SEQ;
;     int krow[3], kcol[3];
; #pragma unroll
;     for (int e = 0; e < 3; ++e) { const int c = tid + 512 * e; krow[e] = c / 24; kcol[e] = c % 24; }
;     u32x4 pk[3], pv[2];
;     ...
;     AT_LOAD(0); AT_WRITE(0);
;     __syncthreads();
	ds_write_b128 v36, v[2:5]
	v_add3_u32 v2, 0, v209, v210
	s_waitcnt vmcnt(9)
	ds_write_b128 v2, v[6:9]
	v_add3_u32 v2, 0, v211, v212
	v_lshlrev_b32_e32 v3, 4, v33
	v_mov_b32_e32 v6, v1
	s_waitcnt vmcnt(8)
	ds_write_b128 v2, v[10:13]
	v_add3_u32 v2, v213, v214, s65
	v_mov_b32_e32 v7, v1
	v_mov_b32_e32 v8, v1
	v_mov_b32_e32 v9, v1
	s_waitcnt vmcnt(7)
	ds_write2_b64 v2, v[14:15], v[16:17] offset1:2
	v_add3_u32 v2, v213, v215, s65
	v_mov_b32_e32 v14, v1
	v_mov_b32_e32 v15, v1
	s_waitcnt vmcnt(6)
	ds_write2_b64 v2, v[18:19], v[20:21] offset1:2
	v_or_b32_e32 v2, s56, v29
	v_mul_lo_u32 v2, v2, s77
	v_add3_u32 v216, 0, v2, v3
	v_mul_u32_u24_e32 v2, 0x90, v29
	v_lshlrev_b32_e32 v3, 2, v182
	v_lshl_add_u32 v3, s56, 1, v3
	v_add3_u32 v206, 0, v2, v3
	v_sub_u32_e32 v2, v205, v182
	v_subrev_u32_e32 v217, s56, v2
	v_lshl_add_u64 v[2:3], v[30:31], 0, s[92:93]
	v_lshl_add_u64 v[184:185], v[2:3], 0, s[0:1]
	v_lshl_add_u64 v[2:3], v[34:35], 0, s[92:93]
	v_lshl_add_u64 v[186:187], v[2:3], 0, s[0:1]
	v_mov_b64_e32 v[2:3], s[54:55]
	v_mad_i64_i32 v[4:5], s[0:1], v44, s76, v[2:3]
	v_mad_u64_u32 v[4:5], s[0:1], s2, v0, v[4:5]
	v_lshl_add_u64 v[188:189], v[4:5], 0, v[26:27]
	v_mad_i64_i32 v[4:5], s[0:1], v42, s76, v[2:3]
	v_mad_i64_i32 v[2:3], s[0:1], v40, s76, v[2:3]
	v_mad_u64_u32 v[4:5], s[0:1], s2, v0, v[4:5]
	v_mad_u64_u32 v[2:3], s[0:1], s2, v0, v[2:3]
	v_lshl_add_u64 v[190:191], v[4:5], 0, v[24:25]
	v_lshl_add_u64 v[192:193], v[2:3], 0, v[22:23]
	v_mov_b32_e32 v0, v1
	v_mov_b32_e32 v2, v1
	v_mov_b32_e32 v3, v1
	v_mov_b32_e32 v4, v1
	v_mov_b32_e32 v5, v1
	v_mov_b32_e32 v10, v1
	v_mov_b32_e32 v11, v1
	v_mov_b32_e32 v12, v1
	v_mov_b32_e32 v13, v1
	v_mov_b64_e32 v[64:65], v[14:15]
	v_mov_b64_e32 v[48:49], v[14:15]
	v_mov_b64_e32 v[32:33], v[14:15]
	v_mov_b64_e32 v[62:63], v[12:13]
	v_mov_b64_e32 v[60:61], v[10:11]
	v_mov_b64_e32 v[58:59], v[8:9]
	v_mov_b64_e32 v[56:57], v[6:7]
	v_mov_b64_e32 v[54:55], v[4:5]
	v_mov_b64_e32 v[52:53], v[2:3]
	v_mov_b64_e32 v[50:51], v[0:1]
	v_mov_b64_e32 v[46:47], v[12:13]
	v_mov_b64_e32 v[44:45], v[10:11]
	v_mov_b64_e32 v[42:43], v[8:9]
	v_mov_b64_e32 v[40:41], v[6:7]
	v_mov_b64_e32 v[38:39], v[4:5]
	v_mov_b64_e32 v[36:37], v[2:3]
	v_mov_b64_e32 v[34:35], v[0:1]
	v_mov_b64_e32 v[30:31], v[12:13]
	v_mov_b64_e32 v[28:29], v[10:11]
	v_mov_b64_e32 v[26:27], v[8:9]
	v_mov_b64_e32 v[24:25], v[6:7]
	v_mov_b64_e32 v[22:23], v[4:5]
	v_mov_b64_e32 v[20:21], v[2:3]
	v_mov_b64_e32 v[18:19], v[0:1]
	v_mov_b64_e32 v[16:17], v[14:15]
	v_mov_b64_e32 v[14:15], v[12:13]
	v_mov_b64_e32 v[12:13], v[10:11]
	v_mov_b64_e32 v[10:11], v[8:9]
	v_mov_b64_e32 v[8:9], v[6:7]
	v_mov_b64_e32 v[6:7], v[4:5]
	v_mov_b64_e32 v[4:5], v[2:3]
	v_mov_b64_e32 v[2:3], v[0:1]
	s_waitcnt vmcnt(5)
	ds_write_b128 v66, v[130:133]
	s_waitcnt vmcnt(4)
	ds_write_b128 v67, v[134:137]
	s_waitcnt vmcnt(3)
	ds_write_b128 v68, v[138:141]
	s_waitcnt vmcnt(2)
	ds_write_b128 v69, v[142:145]
	s_waitcnt vmcnt(1)
	ds_write_b128 v70, v[146:149]
	s_waitcnt vmcnt(0)
	ds_write_b128 v71, v[150:153]
	s_waitcnt lgkmcnt(0)
	s_barrier
	v_lshrrev_b32_e32 v78, 5, v183
	v_and_b32_e32 v79, 31, v183
	v_mul_u32_u24_e32 v79, s77, v79
	v_lshl_add_u32 v79, v78, 4, v79
	s_mul_i32 vcc_lo, s20, 0x3200
	s_add_u32 vcc_lo, vcc_lo, 0x15800
	v_add_u32_e32 v79, vcc_lo, v79
	ds_read_b128 v[126:129], v79
	ds_read_b128 v[122:125], v79 offset:32
	ds_read_b128 v[118:121], v79 offset:64
	ds_read_b128 v[114:117], v79 offset:96
	ds_read_b128 v[110:113], v79 offset:128
	ds_read_b128 v[106:109], v79 offset:160
	ds_read_b128 v[102:105], v79 offset:192
	ds_read_b128 v[98:101], v79 offset:224
	ds_read_b128 v[94:97], v79 offset:256
	ds_read_b128 v[90:93], v79 offset:288
	ds_read_b128 v[86:89], v79 offset:320
	ds_read_b128 v[82:85], v79 offset:352
	s_waitcnt vmcnt(0)
	v_mov_b64_e32 v[230:231], 0
	v_mov_b64_e32 v[232:233], 0
	v_mov_b64_e32 v[234:235], 0
	v_mov_b64_e32 v[236:237], 0
	v_mov_b64_e32 v[238:239], 0
	v_mov_b64_e32 v[240:241], 0
	v_mov_b64_e32 v[242:243], 0
	v_mov_b64_e32 v[244:245], 0
	v_mov_b32_e32 v246, 0xff800000
	v_lshl_add_u32 v222, s3, 6, v183
	v_and_b32_e32 v222, 0xff, v222
	s_movk_i32 s0, 0x600
	s_movk_i32 s1, 0x190
	s_cmp_lg_u32 s21, 0
	s_cbranch_scc1 .Lal1_b
	v_mov_b32_e32 v223, v222
	v_mul_u32_u24_e32 v224, 0xaaab, v223
	v_lshrrev_b32_e32 v224, 20, v224
	v_mul_u32_u24_e32 v225, 24, v224
	v_sub_u32_e32 v225, v223, v225
	v_lshlrev_b32_e32 v225, 4, v225
	v_mad_u32_u24 v184, v224, s0, v225
	v_mad_u32_u24 v190, v224, s1, v225
	v_add_u32_e32 v223, 256, v222
	v_mul_u32_u24_e32 v224, 0xaaab, v223
	v_lshrrev_b32_e32 v224, 20, v224
	v_mul_u32_u24_e32 v225, 24, v224
	v_sub_u32_e32 v225, v223, v225
	v_lshlrev_b32_e32 v225, 4, v225
	v_mad_u32_u24 v185, v224, s0, v225
	v_mad_u32_u24 v191, v224, s1, v225
	v_add_u32_e32 v223, 512, v222
	v_mul_u32_u24_e32 v224, 0xaaab, v223
	v_lshrrev_b32_e32 v224, 20, v224
	v_mul_u32_u24_e32 v225, 24, v224
	v_sub_u32_e32 v225, v223, v225
	v_lshlrev_b32_e32 v225, 4, v225
	v_mad_u32_u24 v186, v224, s0, v225
	v_mad_u32_u24 v192, v224, s1, v225
	v_add_u32_e32 v223, 768, v222
	v_mul_u32_u24_e32 v224, 0xaaab, v223
	v_lshrrev_b32_e32 v224, 20, v224
	v_mul_u32_u24_e32 v225, 24, v224
	v_sub_u32_e32 v225, v223, v225
	v_lshlrev_b32_e32 v225, 4, v225
	v_mad_u32_u24 v187, v224, s0, v225
	v_mad_u32_u24 v193, v224, s1, v225
	v_add_u32_e32 v223, 1024, v222
	v_mul_u32_u24_e32 v224, 0xaaab, v223
	v_lshrrev_b32_e32 v224, 20, v224
	v_mul_u32_u24_e32 v225, 24, v224
	v_sub_u32_e32 v225, v223, v225
	v_lshlrev_b32_e32 v225, 4, v225
	v_mad_u32_u24 v188, v224, s0, v225
	v_mad_u32_u24 v207, v224, s1, v225
	v_add_u32_e32 v223, 1280, v222
	v_mul_u32_u24_e32 v224, 0xaaab, v223
	v_lshrrev_b32_e32 v224, 20, v224
	v_mul_u32_u24_e32 v225, 24, v224
	v_sub_u32_e32 v225, v223, v225
	v_lshlrev_b32_e32 v225, 4, v225
	v_mad_u32_u24 v189, v224, s0, v225
	v_mad_u32_u24 v208, v224, s1, v225
	s_branch .Lal1_done

; #define AT_LOAD(st) do { _Pragma("unroll") for (int e = 0; e < 3; ++e) pk[e] = *(const u32x4*)(kbase + (size_t)((st) * 64 + krow[e]) * 768 + kcol[e] * 8); \
;         _Pragma("unroll") for (int e = 0; e < 2; ++e) { const int c = tid + 512 * e; pv[e] = *(const u32x4*)(vbase + (size_t)(c >> 3) * SEQ + (st) * 64 + (c & 7) * 8); } } while (0)
; DI void attn_unit(const Params& p, int b, int h, int qb, LAS unsigned char* lds, int tid, int lane, int wave) {
;     ...
;     AT_LOAD(0); AT_WRITE(0);
;     __syncthreads();
;     for (int st = 0; st < nst; ++st) {
.Lal1_done:
	s_waitcnt lgkmcnt(0)
	s_mul_i32 s0, s66, 0x600
	s_mul_i32 s1, s2, 0x180
	s_add_u32 s0, s0, s1
	s_add_u32 s0, s0, 0xce18000
	s_add_u32 s98, s0, s50
	s_addc_u32 s99, 0, s51
	s_add_u32 s0, s92, 0xe600080
	s_add_u32 s100, s0, s50
	s_addc_u32 s101, 0, s51
	s_branch .LBB0_429

; #define AT_LOAD(st) do { _Pragma("unroll") for (int e = 0; e < 3; ++e) pk[e] = *(const u32x4*)(kbase + (size_t)((st) * 64 + krow[e]) * 768 + kcol[e] * 8); \
;         _Pragma("unroll") for (int e = 0; e < 2; ++e) { const int c = tid + 512 * e; pv[e] = *(const u32x4*)(vbase + (size_t)(c >> 3) * SEQ + (st) * 64 + (c & 7) * 8); } } while (0)
; DI void attn_unit(const Params& p, int b, int h, int qb, LAS unsigned char* lds, int tid, int lane, int wave) {
;     ...
;     const int g = wave >> 2, w4 = wave & 3, r = lane & 31, hh = lane >> 5;
;     const int qr0 = qb * 128 + w4 * 32, nst = 2 * (qb + 1);
;     const size_t tokb = (size_t)b * SEQ;
;     bf16x8 qf[12];
;     { const bf16_t* qp = Q + (tokb + qr0 + r) * 768 + h * 192 + 8 * hh;
; #pragma unroll
;       for (int kk = 0; kk < 12; ++kk) qf[kk] = *(const bf16x8*)(qp + 16 * kk); }
;     f32x16 o[4];
; #pragma unroll
;     for (int i = 0; i < 4; ++i)
; #pragma unroll
;         for (int j = 0; j < 16; ++j) o[i][j] = 0.f;
;     float mrow = -INFINITY, lrow = 0.f;
;     const bf16_t* kbase = KB + tokb * 768 + h * 192;
;     const bf16_t* vbase = VT + (size_t)((b * 4 + h) * 128) * SEQ;
;     int krow[3], kcol[3];
; #pragma unroll
;     for (int e = 0; e < 3; ++e) { const int c = tid + 512 * e; krow[e] = c / 24; kcol[e] = c % 24; }
;     u32x4 pk[3], pv[2];
;     ...
;     AT_LOAD(0); AT_WRITE(0);
.LBB0_444:
	s_mov_b32 s3, s33
	s_mov_b64 s[0:1], s[50:51]
	s_barrier
	v_mbcnt_lo_u32_b32 v183, -1, 0
	v_mbcnt_hi_u32_b32 v183, -1, v183
	s_mov_b32 s0, 0x2aaaaaab
	v_lshl_add_u32 v14, s3, 6, v183
	v_mul_hi_i32 v0, v14, s0
	v_lshrrev_b32_e32 v2, 31, v0
	v_ashrrev_i32_e32 v0, 2, v0
	v_add_u32_e32 v40, v0, v2
	v_mul_lo_u32 v0, v40, 24
	v_add_u32_e32 v20, 0x200, v14
	v_sub_u32_e32 v41, v14, v0
	v_mul_hi_i32 v0, v20, s0
	v_lshrrev_b32_e32 v2, 31, v0
	v_ashrrev_i32_e32 v0, 2, v0
	v_add_u32_e32 v42, v0, v2
	v_mul_lo_u32 v0, v42, 24
	v_sub_u32_e32 v43, v20, v0
	v_add_u32_e32 v0, 0x400, v14
	v_mul_hi_i32 v2, v0, s0
	v_lshrrev_b32_e32 v3, 31, v2
	v_ashrrev_i32_e32 v2, 2, v2
	v_add_u32_e32 v44, v2, v3
	v_mul_lo_u32 v2, v44, 24
	v_sub_u32_e32 v45, v0, v2
	v_lshlrev_b32_e32 v4, 3, v41
	v_lshlrev_b32_e32 v6, 3, v43
	v_mov_b64_e32 v[10:11], s[52:53]
	v_ashrrev_i32_e32 v5, 31, v4
	v_ashrrev_i32_e32 v7, 31, v6
	v_lshlrev_b32_e32 v12, 3, v45
	v_mad_i64_i32 v[2:3], s[0:1], v40, s76, v[10:11]
	v_lshlrev_b64 v[22:23], 1, v[4:5]
	v_mad_i64_i32 v[4:5], s[0:1], v42, s76, v[10:11]
	v_lshlrev_b64 v[24:25], 1, v[6:7]
	v_ashrrev_i32_e32 v13, 31, v12
	v_lshlrev_b32_e32 v0, 4, v183
	v_ashrrev_i32_e32 v28, 3, v14
	v_lshl_add_u64 v[2:3], v[2:3], 0, v[22:23]
	v_lshl_add_u64 v[6:7], v[4:5], 0, v[24:25]
	v_mad_i64_i32 v[10:11], s[0:1], v44, s76, v[10:11]
	v_lshlrev_b64 v[26:27], 1, v[12:13]
	v_and_b32_e32 v0, 0x70, v0
	v_ashrrev_i32_e32 v29, 31, v28
	v_ashrrev_i32_e32 v32, 3, v20
	global_load_dwordx4 v[2:5], v[2:3], off
	s_nop 0
	global_load_dwordx4 v[6:9], v[6:7], off
	v_lshl_add_u64 v[10:11], v[10:11], 0, v[26:27]
	v_lshl_add_u64 v[18:19], s[74:75], 0, v[0:1]
	v_lshlrev_b64 v[30:31], 13, v[28:29]
	v_ashrrev_i32_e32 v33, 31, v32
	s_and_b32 s0, s72, 15
	s_and_b32 s20, s3, 3
	global_load_dwordx4 v[10:13], v[10:11], off
	v_lshl_add_u64 v[14:15], v[18:19], 0, v[30:31]
	v_lshlrev_b64 v[34:35], 13, v[32:33]
	s_lshl_b32 s4, s0, 7
	s_lshl_b32 s0, s94, 7
	s_lshl_b32 s5, s20, 5
	global_load_dwordx4 v[14:17], v[14:15], off
	v_lshl_add_u64 v[18:19], v[18:19], 0, v[34:35]
	v_and_b32_e32 v205, 31, v183
	s_or_b32 s36, s5, s0
	v_readlane_b32 s0, v254, 48
	global_load_dwordx4 v[18:21], v[18:19], off
	v_or_b32_e32 v33, s66, v205
	v_readlane_b32 s1, v254, 49
	v_or_b32_e32 v202, s36, v33
	v_ashrrev_i32_e32 v29, 5, v183
	v_mov_b64_e32 v[36:37], s[0:1]
	v_mad_u64_u32 v[36:37], s[0:1], v202, s76, v[36:37]
	s_lshl_b32 s0, s67, 1
	s_mov_b32 s1, s93
	v_lshlrev_b32_e32 v38, 3, v29
	v_lshl_add_u64 v[36:37], v[36:37], 0, s[0:1]
	v_ashrrev_i32_e32 v39, 31, v38
	v_lshl_add_u64 v[36:37], v[38:39], 1, v[36:37]
	v_readfirstlane_b32 s0, v36
	v_readfirstlane_b32 s1, v37
	s_lshr_b32 vcc_hi, s3, 2
	s_mul_i32 vcc_lo, s20, 0x3200
	s_add_u32 vcc_lo, vcc_lo, 0x15800
	s_mulk_i32 vcc_hi, 0x180
	v_add_u32_e32 v78, vcc_hi, v183
	v_mul_u32_u24_e32 v79, 0xaaab, v78
	v_lshrrev_b32_e32 v79, 20, v79
	v_mul_u32_u24_e32 v80, 24, v79
	v_sub_u32_e32 v80, v78, v80
	v_lshlrev_b32_e32 v80, 4, v80
	v_mad_u32_u24 v81, v79, s76, v80
	v_mad_u32_u24 v66, v79, s77, v80
	v_add_u32_e32 v66, vcc_lo, v66
	global_load_dwordx4 v[130:133], v81, s[0:1]
	v_add_u32_e32 v78, 64, v78
	v_mul_u32_u24_e32 v79, 0xaaab, v78
	v_lshrrev_b32_e32 v79, 20, v79
	v_mul_u32_u24_e32 v80, 24, v79
	v_sub_u32_e32 v80, v78, v80
	v_lshlrev_b32_e32 v80, 4, v80
	v_mad_u32_u24 v81, v79, s76, v80
	v_mad_u32_u24 v67, v79, s77, v80
	v_add_u32_e32 v67, vcc_lo, v67
	global_load_dwordx4 v[134:137], v81, s[0:1]
	v_add_u32_e32 v78, 64, v78
	v_mul_u32_u24_e32 v79, 0xaaab, v78
	v_lshrrev_b32_e32 v79, 20, v79
	v_mul_u32_u24_e32 v80, 24, v79
	v_sub_u32_e32 v80, v78, v80
	v_lshlrev_b32_e32 v80, 4, v80
	v_mad_u32_u24 v81, v79, s76, v80
	v_mad_u32_u24 v68, v79, s77, v80
	v_add_u32_e32 v68, vcc_lo, v68
	global_load_dwordx4 v[138:141], v81, s[0:1]
	v_add_u32_e32 v78, 64, v78
	v_mul_u32_u24_e32 v79, 0xaaab, v78
	v_lshrrev_b32_e32 v79, 20, v79
	v_mul_u32_u24_e32 v80, 24, v79
	v_sub_u32_e32 v80, v78, v80
	v_lshlrev_b32_e32 v80, 4, v80
	v_mad_u32_u24 v81, v79, s76, v80
	v_mad_u32_u24 v69, v79, s77, v80
	v_add_u32_e32 v69, vcc_lo, v69
	global_load_dwordx4 v[142:145], v81, s[0:1]
	v_add_u32_e32 v78, 64, v78
	v_mul_u32_u24_e32 v79, 0xaaab, v78
	v_lshrrev_b32_e32 v79, 20, v79
	v_mul_u32_u24_e32 v80, 24, v79
	v_sub_u32_e32 v80, v78, v80
	v_lshlrev_b32_e32 v80, 4, v80
	v_mad_u32_u24 v81, v79, s76, v80
	v_mad_u32_u24 v70, v79, s77, v80
	v_add_u32_e32 v70, vcc_lo, v70
	global_load_dwordx4 v[146:149], v81, s[0:1]
	v_add_u32_e32 v78, 64, v78
	v_mul_u32_u24_e32 v79, 0xaaab, v78
	v_lshrrev_b32_e32 v79, 20, v79
	v_mul_u32_u24_e32 v80, 24, v79
	v_sub_u32_e32 v80, v78, v80
	v_lshlrev_b32_e32 v80, 4, v80
	v_mad_u32_u24 v81, v79, s76, v80
	v_mad_u32_u24 v71, v79, s77, v80
	v_add_u32_e32 v71, vcc_lo, v71
	global_load_dwordx4 v[150:153], v81, s[0:1]
	v_mul_lo_u32 v207, v40, s77
	v_lshlrev_b32_e32 v208, 4, v41
	v_add3_u32 v33, 0, v207, v208
	v_mul_lo_u32 v209, v42, s77
	v_lshlrev_b32_e32 v210, 4, v43
	v_mul_lo_u32 v211, v44, s77
	v_lshlrev_b32_e32 v212, 4, v45
	s_movk_i32 s0, 0x90
	v_bfe_u32 v222, v0, 4, 1
	v_and_b32_e32 v213, 0x60, v0
	v_lshl_or_b32 v213, v222, 3, v213
	v_mul_lo_u32 v214, v28, s0
	s_ashr_i32 s21, s3, 2
	v_mul_lo_u32 v215, v32, s0
	s_lshl_b32 s53, s21, 5
	v_lshlrev_b32_e32 v182, 2, v29
	s_or_b32 s0, s4, s5
	v_or_b32_e32 v30, v30, v0
	v_or_b32_e32 v34, v34, v0
	s_or_b32 s52, s4, 64
	s_or_b32 s56, s36, 31
	v_mov_b32_e32 v0, v1
	v_mov_b32_e32 v203, 0
	v_mov_b32_e32 v204, 0xff800000
	s_waitcnt vmcnt(10)
	ds_write_b128 v33, v[2:5]
	v_add3_u32 v2, 0, v209, v210
	s_waitcnt vmcnt(9)
	ds_write_b128 v2, v[6:9]
	v_add3_u32 v2, 0, v211, v212
	v_lshlrev_b32_e32 v3, 4, v29
	v_mov_b32_e32 v6, v1
	v_mov_b32_e32 v7, v1
	v_mov_b32_e32 v8, v1
	s_waitcnt vmcnt(8)
; #define AT_LOAD(st) do { _Pragma("unroll") for (int e = 0; e < 3; ++e) pk[e] = *(const u32x4*)(kbase + (size_t)((st) * 64 + krow[e]) * 768 + kcol[e] * 8); \
;         _Pragma("unroll") for (int e = 0; e < 2; ++e) { const int c = tid + 512 * e; pv[e] = *(const u32x4*)(vbase + (size_t)(c >> 3) * SEQ + (st) * 64 + (c & 7) * 8); } } while (0)
; DI void attn_unit(const Params& p, int b, int h, int qb, LAS unsigned char* lds, int tid, int lane, int wave) {
;     ...
;     bf16x8 qf[12];
;     { const bf16_t* qp = Q + (tokb + qr0 + r) * 768 + h * 192 + 8 * hh;
; #pragma unroll
;       for (int kk = 0; kk < 12; ++kk) qf[kk] = *(const bf16x8*)(qp + 16 * kk); }
;     f32x16 o[4];
; #pragma unroll
;     for (int i = 0; i < 4; ++i)
; #pragma unroll
;         for (int j = 0; j < 16; ++j) o[i][j] = 0.f;
;     float mrow = -INFINITY, lrow = 0.f;
;     const bf16_t* kbase = KB + tokb * 768 + h * 192;
;     const bf16_t* vbase = VT + (size_t)((b * 4 + h) * 128) * SEQ;
;     int krow[3], kcol[3];
; #pragma unroll
;     for (int e = 0; e < 3; ++e) { const int c = tid + 512 * e; krow[e] = c / 24; kcol[e] = c % 24; }
;     u32x4 pk[3], pv[2];
;     ...
;     AT_LOAD(0); AT_WRITE(0);
;     __syncthreads();
	ds_write_b128 v2, v[10:13]
	v_add3_u32 v2, v213, v214, s65
	v_mov_b32_e32 v9, v1
	v_mov_b32_e32 v10, v1
	v_mov_b32_e32 v11, v1
	v_mov_b32_e32 v12, v1
	s_waitcnt vmcnt(7)
	ds_write2_b64 v2, v[14:15], v[16:17] offset1:2
	v_add3_u32 v2, v213, v215, s65
	v_mov_b32_e32 v14, v1
	v_mov_b32_e32 v15, v1
	v_mov_b32_e32 v13, v1
	s_waitcnt vmcnt(6)
	ds_write2_b64 v2, v[18:19], v[20:21] offset1:2
	v_or_b32_e32 v2, s53, v205
	v_mul_lo_u32 v2, v2, s77
	v_add3_u32 v216, 0, v2, v3
	v_mul_u32_u24_e32 v2, 0x90, v205
	v_lshlrev_b32_e32 v3, 2, v182
	v_lshl_add_u32 v3, s53, 1, v3
	v_add3_u32 v206, 0, v2, v3
	v_or_b32_e32 v2, s0, v205
	v_sub_u32_e32 v2, v2, v182
	v_subrev_u32_e32 v217, s53, v2
	v_lshl_add_u64 v[2:3], v[30:31], 0, s[92:93]
	s_mov_b64 s[0:1], 0xe600080
	v_lshl_add_u64 v[184:185], v[2:3], 0, s[0:1]
	v_lshl_add_u64 v[2:3], v[34:35], 0, s[92:93]
	v_lshl_add_u64 v[186:187], v[2:3], 0, s[0:1]
	s_mul_i32 s0, s2, 0x180
	s_add_u32 s0, s0, s54
	s_addc_u32 s1, 0, s55
	v_mov_b64_e32 v[2:3], s[0:1]
	v_mad_i64_i32 v[4:5], s[0:1], v44, s76, v[2:3]
	v_lshl_add_u64 v[188:189], v[4:5], 0, v[26:27]
	v_mad_i64_i32 v[4:5], s[0:1], v42, s76, v[2:3]
	v_mad_i64_i32 v[2:3], s[0:1], v40, s76, v[2:3]
	v_lshl_add_u64 v[190:191], v[4:5], 0, v[24:25]
	v_lshl_add_u64 v[192:193], v[2:3], 0, v[22:23]
	v_mov_b32_e32 v2, v1
	v_mov_b32_e32 v3, v1
	v_mov_b32_e32 v4, v1
	v_mov_b32_e32 v5, v1
	v_mov_b64_e32 v[64:65], v[14:15]
	v_mov_b64_e32 v[48:49], v[14:15]
	v_mov_b64_e32 v[32:33], v[14:15]
	v_mov_b64_e32 v[62:63], v[12:13]
	v_mov_b64_e32 v[60:61], v[10:11]
	v_mov_b64_e32 v[58:59], v[8:9]
	v_mov_b64_e32 v[56:57], v[6:7]
	v_mov_b64_e32 v[54:55], v[4:5]
	v_mov_b64_e32 v[52:53], v[2:3]
	v_mov_b64_e32 v[50:51], v[0:1]
	v_mov_b64_e32 v[46:47], v[12:13]
	v_mov_b64_e32 v[44:45], v[10:11]
	v_mov_b64_e32 v[42:43], v[8:9]
	v_mov_b64_e32 v[40:41], v[6:7]
	v_mov_b64_e32 v[38:39], v[4:5]
	v_mov_b64_e32 v[36:37], v[2:3]
	v_mov_b64_e32 v[34:35], v[0:1]
	v_mov_b64_e32 v[30:31], v[12:13]
	v_mov_b64_e32 v[28:29], v[10:11]
	v_mov_b64_e32 v[26:27], v[8:9]
	v_mov_b64_e32 v[24:25], v[6:7]
	v_mov_b64_e32 v[22:23], v[4:5]
	v_mov_b64_e32 v[20:21], v[2:3]
	v_mov_b64_e32 v[18:19], v[0:1]
	v_mov_b64_e32 v[16:17], v[14:15]
	s_mov_b32 s54, 0
	v_mov_b64_e32 v[14:15], v[12:13]
	v_mov_b64_e32 v[12:13], v[10:11]
	v_mov_b64_e32 v[10:11], v[8:9]
	v_mov_b64_e32 v[8:9], v[6:7]
	v_mov_b64_e32 v[6:7], v[4:5]
	v_mov_b64_e32 v[4:5], v[2:3]
	v_mov_b64_e32 v[2:3], v[0:1]
	s_mov_b32 s55, 0
	s_waitcnt vmcnt(5)
	ds_write_b128 v66, v[130:133]
	s_waitcnt vmcnt(4)
	ds_write_b128 v67, v[134:137]
	s_waitcnt vmcnt(3)
	ds_write_b128 v68, v[138:141]
	s_waitcnt vmcnt(2)
	ds_write_b128 v69, v[142:145]
	s_waitcnt vmcnt(1)
	ds_write_b128 v70, v[146:149]
	s_waitcnt vmcnt(0)
	ds_write_b128 v71, v[150:153]
	s_waitcnt lgkmcnt(0)
	s_barrier
	v_lshrrev_b32_e32 v78, 5, v183
	v_and_b32_e32 v79, 31, v183
	v_mul_u32_u24_e32 v79, s77, v79
	v_lshl_add_u32 v79, v78, 4, v79
	s_mul_i32 vcc_lo, s20, 0x3200
	s_add_u32 vcc_lo, vcc_lo, 0x15800
	v_add_u32_e32 v79, vcc_lo, v79
	ds_read_b128 v[126:129], v79
	ds_read_b128 v[122:125], v79 offset:32
	ds_read_b128 v[118:121], v79 offset:64
	ds_read_b128 v[114:117], v79 offset:96
	ds_read_b128 v[110:113], v79 offset:128
	ds_read_b128 v[106:109], v79 offset:160
	ds_read_b128 v[102:105], v79 offset:192
	ds_read_b128 v[98:101], v79 offset:224
	ds_read_b128 v[94:97], v79 offset:256
	ds_read_b128 v[90:93], v79 offset:288
	ds_read_b128 v[86:89], v79 offset:320
	ds_read_b128 v[82:85], v79 offset:352
	s_waitcnt vmcnt(0)
	v_mov_b64_e32 v[230:231], 0
	v_mov_b64_e32 v[232:233], 0
	v_mov_b64_e32 v[234:235], 0
	v_mov_b64_e32 v[236:237], 0
	v_mov_b64_e32 v[238:239], 0
	v_mov_b64_e32 v[240:241], 0
	v_mov_b64_e32 v[242:243], 0
	v_mov_b64_e32 v[244:245], 0
	v_mov_b32_e32 v246, 0xff800000
	v_lshl_add_u32 v222, s3, 6, v183
	v_and_b32_e32 v222, 0xff, v222
	s_movk_i32 s0, 0x600
	s_movk_i32 s1, 0x190
	s_cmp_lg_u32 s21, 0
	s_cbranch_scc1 .Lal2_b
	v_mov_b32_e32 v223, v222
	v_mul_u32_u24_e32 v224, 0xaaab, v223
	v_lshrrev_b32_e32 v224, 20, v224
	v_mul_u32_u24_e32 v225, 24, v224
	v_sub_u32_e32 v225, v223, v225
	v_lshlrev_b32_e32 v225, 4, v225
	v_mad_u32_u24 v184, v224, s0, v225
	v_mad_u32_u24 v190, v224, s1, v225
	v_add_u32_e32 v223, 256, v222
	v_mul_u32_u24_e32 v224, 0xaaab, v223
	v_lshrrev_b32_e32 v224, 20, v224
	v_mul_u32_u24_e32 v225, 24, v224
	v_sub_u32_e32 v225, v223, v225
	v_lshlrev_b32_e32 v225, 4, v225
	v_mad_u32_u24 v185, v224, s0, v225
	v_mad_u32_u24 v191, v224, s1, v225
	v_add_u32_e32 v223, 512, v222
	v_mul_u32_u24_e32 v224, 0xaaab, v223
	v_lshrrev_b32_e32 v224, 20, v224
	v_mul_u32_u24_e32 v225, 24, v224
	v_sub_u32_e32 v225, v223, v225
	v_lshlrev_b32_e32 v225, 4, v225
	v_mad_u32_u24 v186, v224, s0, v225
	v_mad_u32_u24 v192, v224, s1, v225
	v_add_u32_e32 v223, 768, v222
	v_mul_u32_u24_e32 v224, 0xaaab, v223
	v_lshrrev_b32_e32 v224, 20, v224
	v_mul_u32_u24_e32 v225, 24, v224
	v_sub_u32_e32 v225, v223, v225
	v_lshlrev_b32_e32 v225, 4, v225
	v_mad_u32_u24 v187, v224, s0, v225
	v_mad_u32_u24 v193, v224, s1, v225
	v_add_u32_e32 v223, 1024, v222
	v_mul_u32_u24_e32 v224, 0xaaab, v223
	v_lshrrev_b32_e32 v224, 20, v224
	v_mul_u32_u24_e32 v225, 24, v224
	v_sub_u32_e32 v225, v223, v225
	v_lshlrev_b32_e32 v225, 4, v225
	v_mad_u32_u24 v188, v224, s0, v225
	v_mad_u32_u24 v207, v224, s1, v225
	v_add_u32_e32 v223, 1280, v222
	v_mul_u32_u24_e32 v224, 0xaaab, v223
	v_lshrrev_b32_e32 v224, 20, v224
	v_mul_u32_u24_e32 v225, 24, v224
	v_sub_u32_e32 v225, v223, v225
	v_lshlrev_b32_e32 v225, 4, v225
	v_mad_u32_u24 v189, v224, s0, v225
	v_mad_u32_u24 v208, v224, s1, v225
	s_branch .Lal2_done
